# DPP-class cross-lane: EpiRes row-stat butterflies via v_permlane16/32_swap instead of ds_bpermute round trips (bit-identical sums), on v21
# baseline (speedup 1.0000x reference)
.LBB0_815:
	v_mul_f32_e32 v182, v159, v159
	v_add_f32_e32 v175, 0, v158
	v_pk_fma_f32 v[182:183], v[158:159], v[158:159], v[182:183] op_sel_hi:[1,1,0]
	v_add_f32_e32 v175, v159, v175
	v_pk_fma_f32 v[182:183], v[160:161], v[160:161], v[182:183]
	v_mul_f32_e32 v198, v161, v161
	v_add_f32_e32 v175, v160, v175
	v_pk_add_f32 v[182:183], v[198:199], v[182:183] op_sel_hi:[0,1]
	v_add_f32_e32 v175, v161, v175
	v_pk_fma_f32 v[182:183], v[154:155], v[154:155], v[182:183]
	v_mul_f32_e32 v198, v155, v155
	v_add_f32_e32 v175, v154, v175
	v_pk_add_f32 v[182:183], v[198:199], v[182:183] op_sel_hi:[0,1]
	v_add_f32_e32 v175, v155, v175
	v_pk_fma_f32 v[182:183], v[156:157], v[156:157], v[182:183]
	v_mul_f32_e32 v198, v157, v157
	v_add_f32_e32 v175, v156, v175
	v_pk_add_f32 v[182:183], v[198:199], v[182:183] op_sel_hi:[0,1]
	v_add_f32_e32 v175, v157, v175
	v_pk_fma_f32 v[182:183], v[150:151], v[150:151], v[182:183]
	v_mul_f32_e32 v198, v151, v151
	v_add_f32_e32 v175, v150, v175
	v_pk_add_f32 v[182:183], v[198:199], v[182:183] op_sel_hi:[0,1]
	v_add_f32_e32 v175, v151, v175
	v_pk_fma_f32 v[182:183], v[152:153], v[152:153], v[182:183]
	v_mul_f32_e32 v198, v153, v153
	v_add_f32_e32 v175, v152, v175
	v_pk_add_f32 v[182:183], v[198:199], v[182:183] op_sel_hi:[0,1]
	v_add_f32_e32 v175, v153, v175
	v_pk_fma_f32 v[182:183], v[146:147], v[146:147], v[182:183]
	v_mul_f32_e32 v206, v147, v147
	v_add_f32_e32 v175, v146, v175
	v_mov_b32_e32 v202, v148
	v_mov_b32_e32 v203, v147
	v_pk_add_f32 v[182:183], v[206:207], v[182:183] op_sel_hi:[0,1]
	v_add_f32_e32 v175, v147, v175
	v_pk_fma_f32 v[182:183], v[202:203], v[202:203], v[182:183]
	v_pk_mul_f32 v[202:203], v[148:149], v[148:149]
	v_lshl_add_u32 v225, v224, 4, v222
	v_add_f32_e32 v198, v148, v175
	v_pk_mov_b32 v[182:183], v[148:149], v[182:183] op_sel:[1,0]
	v_mov_b32_e32 v199, v203
	v_lshlrev_b32_e32 v175, 2, v225
	v_pk_add_f32 v[182:183], v[182:183], v[198:199]
	v_xor_b32_e32 v227, 64, v175
	v_mov_b32_e32 v198, v182
	v_mov_b32_e32 v199, v183
	s_nop 1
	v_permlane16_swap_b32_e32 v198, v182
	v_permlane16_swap_b32_e32 v199, v183
	v_xor_b32_e32 v228, 0x80, v175
	s_lshl_b32 s30, s42, 3
	s_or_b32 s30, s30, s80
	v_cmp_eq_u32_e64 s[40:41], 0, v224
	s_waitcnt lgkmcnt(0)
	v_pk_add_f32 v[182:183], v[182:183], v[198:199]
	v_mov_b32_e32 v198, v182
	v_mov_b32_e32 v199, v183
	s_nop 1
	v_permlane32_swap_b32_e32 v198, v182
	v_permlane32_swap_b32_e32 v199, v183
	s_ashr_i32 s31, s30, 31
	s_and_saveexec_b64 s[42:43], s[40:41]
	s_cbranch_execz .LBB0_817
	s_waitcnt lgkmcnt(0)
	v_pk_add_f32 v[182:183], v[182:183], v[198:199]
	v_lshlrev_b64 v[198:199], 7, v[176:177]
	v_lshl_add_u64 v[198:199], s[12:13], 0, v[198:199]
	v_lshl_add_u64 v[198:199], s[30:31], 2, v[198:199]
	global_store_dwordx2 v[198:199], v[182:183], off

.LBB0_825:
	v_mul_f32_e32 v184, v143, v143
	v_add_f32_e32 v175, 0, v142
	v_pk_fma_f32 v[184:185], v[142:143], v[142:143], v[184:185] op_sel_hi:[1,1,0]
	v_add_f32_e32 v175, v143, v175
	v_pk_fma_f32 v[184:185], v[144:145], v[144:145], v[184:185]
	v_mul_f32_e32 v196, v145, v145
	v_add_f32_e32 v175, v144, v175
	v_pk_add_f32 v[184:185], v[196:197], v[184:185] op_sel_hi:[0,1]
	v_add_f32_e32 v175, v145, v175
	v_pk_fma_f32 v[184:185], v[138:139], v[138:139], v[184:185]
	v_mul_f32_e32 v196, v139, v139
	v_add_f32_e32 v175, v138, v175
	v_pk_add_f32 v[184:185], v[196:197], v[184:185] op_sel_hi:[0,1]
	v_add_f32_e32 v175, v139, v175
	v_pk_fma_f32 v[184:185], v[140:141], v[140:141], v[184:185]
	v_mul_f32_e32 v196, v141, v141
	v_add_f32_e32 v175, v140, v175
	v_pk_add_f32 v[184:185], v[196:197], v[184:185] op_sel_hi:[0,1]
	v_add_f32_e32 v175, v141, v175
	v_pk_fma_f32 v[184:185], v[134:135], v[134:135], v[184:185]
	v_mul_f32_e32 v196, v135, v135
	v_add_f32_e32 v175, v134, v175
	v_pk_add_f32 v[184:185], v[196:197], v[184:185] op_sel_hi:[0,1]
	v_add_f32_e32 v175, v135, v175
	v_pk_fma_f32 v[184:185], v[136:137], v[136:137], v[184:185]
	v_mul_f32_e32 v196, v137, v137
	v_add_f32_e32 v175, v136, v175
	v_pk_add_f32 v[184:185], v[196:197], v[184:185] op_sel_hi:[0,1]
	v_add_f32_e32 v175, v137, v175
	v_pk_fma_f32 v[184:185], v[130:131], v[130:131], v[184:185]
	v_mul_f32_e32 v204, v131, v131
	v_add_f32_e32 v175, v130, v175
	v_mov_b32_e32 v200, v132
	v_mov_b32_e32 v201, v131
	v_pk_add_f32 v[184:185], v[204:205], v[184:185] op_sel_hi:[0,1]
	v_add_f32_e32 v175, v131, v175
	v_pk_fma_f32 v[184:185], v[200:201], v[200:201], v[184:185]
	v_pk_mul_f32 v[200:201], v[132:133], v[132:133]
	v_add_f32_e32 v196, v132, v175
	v_pk_mov_b32 v[184:185], v[132:133], v[184:185] op_sel:[1,0]
	v_mov_b32_e32 v197, v201
	v_pk_add_f32 v[184:185], v[184:185], v[196:197]
	v_mov_b32_e32 v196, v184
	v_mov_b32_e32 v197, v185
	s_nop 1
	v_permlane16_swap_b32_e32 v196, v184
	v_permlane16_swap_b32_e32 v197, v185
	s_waitcnt lgkmcnt(0)
	v_pk_add_f32 v[184:185], v[184:185], v[196:197]
	v_mov_b32_e32 v196, v184
	v_mov_b32_e32 v197, v185
	s_nop 1
	v_permlane32_swap_b32_e32 v196, v184
	v_permlane32_swap_b32_e32 v197, v185
	s_and_saveexec_b64 s[42:43], s[40:41]
	s_cbranch_execz .LBB0_827
	v_lshlrev_b64 v[180:181], 7, v[180:181]
	v_lshl_add_u64 v[180:181], s[12:13], 0, v[180:181]
	s_waitcnt lgkmcnt(0)
	v_pk_add_f32 v[184:185], v[184:185], v[196:197]
	v_lshl_add_u64 v[180:181], s[30:31], 2, v[180:181]
	global_store_dwordx2 v[180:181], v[184:185], off

.LBB0_835:
	v_mul_f32_e32 v196, v127, v127
	v_add_f32_e32 v175, 0, v126
	v_pk_fma_f32 v[196:197], v[126:127], v[126:127], v[196:197] op_sel_hi:[1,1,0]
	v_add_f32_e32 v175, v127, v175
	v_pk_fma_f32 v[196:197], v[128:129], v[128:129], v[196:197]
	v_mul_f32_e32 v198, v129, v129
	v_add_f32_e32 v175, v128, v175
	v_pk_add_f32 v[196:197], v[198:199], v[196:197] op_sel_hi:[0,1]
	v_add_f32_e32 v175, v129, v175
	v_pk_fma_f32 v[196:197], v[122:123], v[122:123], v[196:197]
	v_mul_f32_e32 v198, v123, v123
	v_add_f32_e32 v175, v122, v175
	v_pk_add_f32 v[196:197], v[198:199], v[196:197] op_sel_hi:[0,1]
	v_add_f32_e32 v175, v123, v175
	v_pk_fma_f32 v[196:197], v[124:125], v[124:125], v[196:197]
	v_mul_f32_e32 v198, v125, v125
	v_add_f32_e32 v175, v124, v175
	v_pk_add_f32 v[196:197], v[198:199], v[196:197] op_sel_hi:[0,1]
	v_add_f32_e32 v175, v125, v175
	v_pk_fma_f32 v[196:197], v[118:119], v[118:119], v[196:197]
	v_mul_f32_e32 v198, v119, v119
	v_add_f32_e32 v175, v118, v175
	v_pk_add_f32 v[196:197], v[198:199], v[196:197] op_sel_hi:[0,1]
	v_add_f32_e32 v175, v119, v175
	v_pk_fma_f32 v[196:197], v[120:121], v[120:121], v[196:197]
	v_mul_f32_e32 v198, v121, v121
	v_add_f32_e32 v175, v120, v175
	v_pk_add_f32 v[196:197], v[198:199], v[196:197] op_sel_hi:[0,1]
	v_add_f32_e32 v175, v121, v175
	v_pk_fma_f32 v[196:197], v[114:115], v[114:115], v[196:197]
	v_mul_f32_e32 v206, v115, v115
	v_add_f32_e32 v175, v114, v175
	v_mov_b32_e32 v202, v116
	v_mov_b32_e32 v203, v115
	v_pk_add_f32 v[196:197], v[206:207], v[196:197] op_sel_hi:[0,1]
	v_add_f32_e32 v175, v115, v175
	v_pk_fma_f32 v[196:197], v[202:203], v[202:203], v[196:197]
	v_pk_mul_f32 v[202:203], v[116:117], v[116:117]
	v_add_f32_e32 v198, v116, v175
	v_pk_mov_b32 v[196:197], v[116:117], v[196:197] op_sel:[1,0]
	v_mov_b32_e32 v199, v203
	v_pk_add_f32 v[196:197], v[196:197], v[198:199]
	v_mov_b32_e32 v198, v196
	v_mov_b32_e32 v199, v197
	s_nop 1
	v_permlane16_swap_b32_e32 v198, v196
	v_permlane16_swap_b32_e32 v199, v197
	s_waitcnt lgkmcnt(0)
	v_pk_add_f32 v[196:197], v[196:197], v[198:199]
	v_mov_b32_e32 v198, v196
	v_mov_b32_e32 v199, v197
	s_nop 1
	v_permlane32_swap_b32_e32 v198, v196
	v_permlane32_swap_b32_e32 v199, v197
	s_and_saveexec_b64 s[42:43], s[40:41]
	s_cbranch_execz .LBB0_837
	v_lshlrev_b64 v[182:183], 7, v[182:183]
	v_lshl_add_u64 v[182:183], s[12:13], 0, v[182:183]
	s_waitcnt lgkmcnt(0)
	v_pk_add_f32 v[196:197], v[196:197], v[198:199]
	v_lshl_add_u64 v[182:183], s[30:31], 2, v[182:183]
	global_store_dwordx2 v[182:183], v[196:197], off

.LBB0_845:
	v_add_f32_e32 v174, 0, v110
	v_add_f32_e32 v177, v111, v174
	v_mul_f32_e32 v174, v111, v111
	v_pk_fma_f32 v[174:175], v[110:111], v[110:111], v[174:175] op_sel_hi:[1,1,0]
	v_mul_f32_e32 v184, v113, v113
	v_pk_fma_f32 v[174:175], v[112:113], v[112:113], v[174:175]
	v_add_f32_e32 v177, v112, v177
	v_pk_add_f32 v[174:175], v[184:185], v[174:175] op_sel_hi:[0,1]
	v_add_f32_e32 v177, v113, v177
	v_pk_fma_f32 v[174:175], v[106:107], v[106:107], v[174:175]
	v_mul_f32_e32 v184, v107, v107
	v_add_f32_e32 v177, v106, v177
	v_pk_add_f32 v[174:175], v[184:185], v[174:175] op_sel_hi:[0,1]
	v_add_f32_e32 v177, v107, v177
	v_pk_fma_f32 v[174:175], v[108:109], v[108:109], v[174:175]
	v_mul_f32_e32 v184, v109, v109
	v_add_f32_e32 v177, v108, v177
	v_pk_add_f32 v[174:175], v[184:185], v[174:175] op_sel_hi:[0,1]
	v_add_f32_e32 v177, v109, v177
	v_pk_fma_f32 v[174:175], v[94:95], v[94:95], v[174:175]
	v_mul_f32_e32 v184, v95, v95
	v_add_f32_e32 v177, v94, v177
	v_pk_add_f32 v[174:175], v[184:185], v[174:175] op_sel_hi:[0,1]
	v_add_f32_e32 v177, v95, v177
	v_pk_fma_f32 v[174:175], v[96:97], v[96:97], v[174:175]
	v_mul_f32_e32 v184, v97, v97
	v_add_f32_e32 v177, v96, v177
	v_pk_add_f32 v[174:175], v[184:185], v[174:175] op_sel_hi:[0,1]
	v_add_f32_e32 v177, v97, v177
	v_pk_fma_f32 v[174:175], v[82:83], v[82:83], v[174:175]
	v_mul_f32_e32 v202, v83, v83
	v_add_f32_e32 v177, v82, v177
	v_mov_b32_e32 v200, v84
	v_mov_b32_e32 v201, v83
	v_pk_add_f32 v[174:175], v[202:203], v[174:175] op_sel_hi:[0,1]
	v_add_f32_e32 v177, v83, v177
	v_pk_fma_f32 v[174:175], v[200:201], v[200:201], v[174:175]
	v_pk_mul_f32 v[200:201], v[84:85], v[84:85]
	v_add_f32_e32 v184, v84, v177
	v_pk_mov_b32 v[174:175], v[84:85], v[174:175] op_sel:[1,0]
	v_mov_b32_e32 v185, v201
	v_pk_add_f32 v[174:175], v[174:175], v[184:185]
	v_mov_b32_e32 v184, v174
	v_mov_b32_e32 v185, v175
	s_nop 1
	v_permlane16_swap_b32_e32 v184, v174
	v_permlane16_swap_b32_e32 v185, v175
	s_waitcnt lgkmcnt(0)
	v_pk_add_f32 v[174:175], v[174:175], v[184:185]
	v_mov_b32_e32 v184, v174
	v_mov_b32_e32 v185, v175
	s_nop 1
	v_permlane32_swap_b32_e32 v184, v174
	v_permlane32_swap_b32_e32 v185, v175
	s_and_saveexec_b64 s[42:43], s[40:41]
	s_cbranch_execz .LBB0_847
	v_lshlrev_b64 v[180:181], 7, v[180:181]
	v_lshl_add_u64 v[180:181], s[12:13], 0, v[180:181]
	s_waitcnt lgkmcnt(0)
	v_pk_add_f32 v[174:175], v[174:175], v[184:185]
	v_lshl_add_u64 v[180:181], s[30:31], 2, v[180:181]
	global_store_dwordx2 v[180:181], v[174:175], off

.LBB0_855:
	v_mul_f32_e32 v196, v63, v63
	v_add_f32_e32 v177, 0, v62
	v_pk_fma_f32 v[196:197], v[62:63], v[62:63], v[196:197] op_sel_hi:[1,1,0]
	v_add_f32_e32 v177, v63, v177
	v_pk_fma_f32 v[196:197], v[64:65], v[64:65], v[196:197]
	v_mul_f32_e32 v198, v65, v65
	v_add_f32_e32 v177, v64, v177
	v_pk_add_f32 v[196:197], v[198:199], v[196:197] op_sel_hi:[0,1]
	v_add_f32_e32 v177, v65, v177
	v_pk_fma_f32 v[196:197], v[58:59], v[58:59], v[196:197]
	v_mul_f32_e32 v198, v59, v59
	v_add_f32_e32 v177, v58, v177
	v_pk_add_f32 v[196:197], v[198:199], v[196:197] op_sel_hi:[0,1]
	v_add_f32_e32 v177, v59, v177
	v_pk_fma_f32 v[196:197], v[60:61], v[60:61], v[196:197]
	v_mul_f32_e32 v198, v61, v61
	v_add_f32_e32 v177, v60, v177
	v_pk_add_f32 v[196:197], v[198:199], v[196:197] op_sel_hi:[0,1]
	v_add_f32_e32 v177, v61, v177
	v_pk_fma_f32 v[196:197], v[54:55], v[54:55], v[196:197]
	v_mul_f32_e32 v198, v55, v55
	v_add_f32_e32 v177, v54, v177
	v_pk_add_f32 v[196:197], v[198:199], v[196:197] op_sel_hi:[0,1]
	v_add_f32_e32 v177, v55, v177
	v_pk_fma_f32 v[196:197], v[56:57], v[56:57], v[196:197]
	v_mul_f32_e32 v198, v57, v57
	v_add_f32_e32 v177, v56, v177
	v_pk_add_f32 v[196:197], v[198:199], v[196:197] op_sel_hi:[0,1]
	v_add_f32_e32 v177, v57, v177
	v_pk_fma_f32 v[196:197], v[50:51], v[50:51], v[196:197]
	v_mul_f32_e32 v204, v51, v51
	v_add_f32_e32 v177, v50, v177
	v_mov_b32_e32 v200, v52
	v_mov_b32_e32 v201, v51
	v_pk_add_f32 v[196:197], v[204:205], v[196:197] op_sel_hi:[0,1]
	v_add_f32_e32 v177, v51, v177
	v_pk_fma_f32 v[196:197], v[200:201], v[200:201], v[196:197]
	v_pk_mul_f32 v[200:201], v[52:53], v[52:53]
	v_add_f32_e32 v198, v52, v177
	v_pk_mov_b32 v[196:197], v[52:53], v[196:197] op_sel:[1,0]
	v_mov_b32_e32 v199, v201
	v_pk_add_f32 v[196:197], v[196:197], v[198:199]
	v_mov_b32_e32 v198, v196
	v_mov_b32_e32 v199, v197
	s_nop 1
	v_permlane16_swap_b32_e32 v198, v196
	v_permlane16_swap_b32_e32 v199, v197
	s_waitcnt lgkmcnt(0)
	v_pk_add_f32 v[196:197], v[196:197], v[198:199]
	v_mov_b32_e32 v198, v196
	v_mov_b32_e32 v199, v197
	s_nop 1
	v_permlane32_swap_b32_e32 v198, v196
	v_permlane32_swap_b32_e32 v199, v197
	s_and_saveexec_b64 s[42:43], s[40:41]
	s_cbranch_execz .LBB0_857
	v_lshlrev_b64 v[182:183], 7, v[182:183]
	v_lshl_add_u64 v[182:183], s[12:13], 0, v[182:183]
	s_waitcnt lgkmcnt(0)
	v_pk_add_f32 v[196:197], v[196:197], v[198:199]
	v_lshl_add_u64 v[182:183], s[30:31], 2, v[182:183]
	global_store_dwordx2 v[182:183], v[196:197], off

.LBB0_865:
	v_mul_f32_e32 v180, v47, v47
	v_add_f32_e32 v177, 0, v46
	v_pk_fma_f32 v[180:181], v[46:47], v[46:47], v[180:181] op_sel_hi:[1,1,0]
	v_add_f32_e32 v177, v47, v177
	v_pk_fma_f32 v[180:181], v[48:49], v[48:49], v[180:181]
	v_mul_f32_e32 v184, v49, v49
	v_add_f32_e32 v177, v48, v177
	v_pk_add_f32 v[180:181], v[184:185], v[180:181] op_sel_hi:[0,1]
	v_add_f32_e32 v177, v49, v177
	v_pk_fma_f32 v[180:181], v[42:43], v[42:43], v[180:181]
	v_mul_f32_e32 v184, v43, v43
	v_add_f32_e32 v177, v42, v177
	v_pk_add_f32 v[180:181], v[184:185], v[180:181] op_sel_hi:[0,1]
	v_add_f32_e32 v177, v43, v177
	v_pk_fma_f32 v[180:181], v[44:45], v[44:45], v[180:181]
	v_mul_f32_e32 v184, v45, v45
	v_add_f32_e32 v177, v44, v177
	v_pk_add_f32 v[180:181], v[184:185], v[180:181] op_sel_hi:[0,1]
	v_add_f32_e32 v177, v45, v177
	v_pk_fma_f32 v[180:181], v[38:39], v[38:39], v[180:181]
	v_mul_f32_e32 v184, v39, v39
	v_add_f32_e32 v177, v38, v177
	v_pk_add_f32 v[180:181], v[184:185], v[180:181] op_sel_hi:[0,1]
	v_add_f32_e32 v177, v39, v177
	v_pk_fma_f32 v[180:181], v[40:41], v[40:41], v[180:181]
	v_mul_f32_e32 v184, v41, v41
	v_add_f32_e32 v177, v40, v177
	v_pk_add_f32 v[180:181], v[184:185], v[180:181] op_sel_hi:[0,1]
	v_add_f32_e32 v177, v41, v177
	v_pk_fma_f32 v[180:181], v[34:35], v[34:35], v[180:181]
	v_mul_f32_e32 v206, v35, v35
	v_add_f32_e32 v177, v34, v177
	v_mov_b32_e32 v202, v36
	v_mov_b32_e32 v203, v35
	v_pk_add_f32 v[180:181], v[206:207], v[180:181] op_sel_hi:[0,1]
	v_add_f32_e32 v177, v35, v177
	v_pk_fma_f32 v[180:181], v[202:203], v[202:203], v[180:181]
	v_pk_mul_f32 v[202:203], v[36:37], v[36:37]
	v_add_f32_e32 v184, v36, v177
	v_pk_mov_b32 v[180:181], v[36:37], v[180:181] op_sel:[1,0]
	v_mov_b32_e32 v185, v203
	v_pk_add_f32 v[180:181], v[180:181], v[184:185]
	v_mov_b32_e32 v184, v180
	v_mov_b32_e32 v185, v181
	s_nop 1
	v_permlane16_swap_b32_e32 v184, v180
	v_permlane16_swap_b32_e32 v185, v181
	s_waitcnt lgkmcnt(0)
	v_pk_add_f32 v[180:181], v[180:181], v[184:185]
	v_mov_b32_e32 v184, v180
	v_mov_b32_e32 v185, v181
	s_nop 1
	v_permlane32_swap_b32_e32 v184, v180
	v_permlane32_swap_b32_e32 v185, v181
	s_and_saveexec_b64 s[42:43], s[40:41]
	s_cbranch_execz .LBB0_867
	v_lshlrev_b64 v[174:175], 7, v[174:175]
	v_lshl_add_u64 v[174:175], s[12:13], 0, v[174:175]
	s_waitcnt lgkmcnt(0)
	v_pk_add_f32 v[180:181], v[180:181], v[184:185]
	v_lshl_add_u64 v[174:175], s[30:31], 2, v[174:175]
	global_store_dwordx2 v[174:175], v[180:181], off

.LBB0_875:
	v_add_f32_e32 v18, 0, v174
	v_add_f32_e32 v20, v175, v18
	v_mul_f32_e32 v18, v175, v175
	v_pk_fma_f32 v[18:19], v[174:175], v[174:175], v[18:19] op_sel_hi:[1,1,0]
	v_add_f32_e32 v20, v176, v20
	v_pk_fma_f32 v[18:19], v[176:177], v[176:177], v[18:19]
	v_add_f32_e32 v21, v177, v20
	v_mul_f32_e32 v20, v177, v177
	v_pk_add_f32 v[18:19], v[20:21], v[18:19] op_sel_hi:[0,1]
	v_add_f32_e32 v20, v178, v21
	v_pk_fma_f32 v[18:19], v[178:179], v[178:179], v[18:19]
	v_add_f32_e32 v21, v179, v20
	v_mul_f32_e32 v20, v179, v179
	v_pk_add_f32 v[18:19], v[20:21], v[18:19] op_sel_hi:[0,1]
	v_add_f32_e32 v20, v180, v21
	v_pk_fma_f32 v[18:19], v[180:181], v[180:181], v[18:19]
	v_add_f32_e32 v21, v181, v20
	v_mul_f32_e32 v20, v181, v181
	v_pk_add_f32 v[18:19], v[20:21], v[18:19] op_sel_hi:[0,1]
	v_add_f32_e32 v20, v182, v21
	v_pk_fma_f32 v[18:19], v[182:183], v[182:183], v[18:19]
	v_add_f32_e32 v21, v183, v20
	v_mul_f32_e32 v20, v183, v183
	v_pk_add_f32 v[18:19], v[20:21], v[18:19] op_sel_hi:[0,1]
	v_add_f32_e32 v20, v184, v21
	v_pk_fma_f32 v[18:19], v[184:185], v[184:185], v[18:19]
	v_add_f32_e32 v21, v185, v20
	v_mul_f32_e32 v20, v185, v185
	v_pk_add_f32 v[18:19], v[20:21], v[18:19] op_sel_hi:[0,1]
	v_pk_fma_f32 v[18:19], v[196:197], v[196:197], v[18:19]
	v_mul_f32_e32 v24, v197, v197
	v_add_f32_e32 v20, v196, v21
	v_mov_b32_e32 v22, v198
	v_mov_b32_e32 v23, v197
	v_pk_add_f32 v[18:19], v[24:25], v[18:19] op_sel_hi:[0,1]
	v_add_f32_e32 v20, v197, v20
	v_pk_fma_f32 v[18:19], v[22:23], v[22:23], v[18:19]
	v_pk_mul_f32 v[22:23], v[198:199], v[198:199]
	v_add_f32_e32 v20, v198, v20
	v_pk_mov_b32 v[18:19], v[198:199], v[18:19] op_sel:[1,0]
	v_mov_b32_e32 v21, v23
	v_pk_add_f32 v[18:19], v[18:19], v[20:21]
	v_mov_b32_e32 v20, v18
	v_mov_b32_e32 v21, v19
	s_nop 1
	v_permlane16_swap_b32_e32 v20, v18
	v_permlane16_swap_b32_e32 v21, v19
	s_waitcnt lgkmcnt(0)
	v_pk_add_f32 v[18:19], v[18:19], v[20:21]
	v_mov_b32_e32 v20, v18
	v_mov_b32_e32 v21, v19
	s_nop 1
	v_permlane32_swap_b32_e32 v20, v18
	v_permlane32_swap_b32_e32 v21, v19
	s_and_saveexec_b64 s[42:43], s[40:41]
	s_cbranch_execz .LBB0_877
	s_waitcnt lgkmcnt(0)
	v_pk_add_f32 v[18:19], v[18:19], v[20:21]
	v_lshlrev_b64 v[20:21], 7, v[200:201]
	v_lshl_add_u64 v[20:21], s[12:13], 0, v[20:21]
	v_lshl_add_u64 v[20:21], s[30:31], 2, v[20:21]
	global_store_dwordx2 v[20:21], v[18:19], off

.LBB0_885:
	v_add_f32_e32 v2, 0, v98
	v_add_f32_e32 v4, v99, v2
	v_mul_f32_e32 v2, v99, v99
	v_pk_fma_f32 v[2:3], v[98:99], v[98:99], v[2:3] op_sel_hi:[1,1,0]
	v_add_f32_e32 v4, v100, v4
	v_pk_fma_f32 v[2:3], v[100:101], v[100:101], v[2:3]
	v_add_f32_e32 v5, v101, v4
	v_mul_f32_e32 v4, v101, v101
	v_pk_add_f32 v[2:3], v[4:5], v[2:3] op_sel_hi:[0,1]
	v_add_f32_e32 v4, v86, v5
	v_pk_fma_f32 v[2:3], v[86:87], v[86:87], v[2:3]
	v_add_f32_e32 v5, v87, v4
	v_mul_f32_e32 v4, v87, v87
	v_pk_add_f32 v[2:3], v[4:5], v[2:3] op_sel_hi:[0,1]
	v_add_f32_e32 v4, v88, v5
	v_pk_fma_f32 v[2:3], v[88:89], v[88:89], v[2:3]
	v_add_f32_e32 v5, v89, v4
	v_mul_f32_e32 v4, v89, v89
	v_pk_add_f32 v[2:3], v[4:5], v[2:3] op_sel_hi:[0,1]
	v_add_f32_e32 v4, v74, v5
	v_pk_fma_f32 v[2:3], v[74:75], v[74:75], v[2:3]
	v_add_f32_e32 v5, v75, v4
	v_mul_f32_e32 v4, v75, v75
	v_pk_add_f32 v[2:3], v[4:5], v[2:3] op_sel_hi:[0,1]
	v_add_f32_e32 v4, v76, v5
	v_pk_fma_f32 v[2:3], v[76:77], v[76:77], v[2:3]
	v_add_f32_e32 v5, v77, v4
	v_mul_f32_e32 v4, v77, v77
	v_pk_add_f32 v[2:3], v[4:5], v[2:3] op_sel_hi:[0,1]
	v_pk_fma_f32 v[2:3], v[66:67], v[66:67], v[2:3]
	v_mul_f32_e32 v8, v67, v67
	v_add_f32_e32 v4, v66, v5
	v_mov_b32_e32 v6, v68
	v_mov_b32_e32 v7, v67
	v_pk_add_f32 v[2:3], v[8:9], v[2:3] op_sel_hi:[0,1]
	v_add_f32_e32 v4, v67, v4
	v_pk_fma_f32 v[2:3], v[6:7], v[6:7], v[2:3]
	v_pk_mul_f32 v[6:7], v[68:69], v[68:69]
	v_add_f32_e32 v4, v68, v4
	v_pk_mov_b32 v[2:3], v[68:69], v[2:3] op_sel:[1,0]
	v_mov_b32_e32 v5, v7
	v_pk_add_f32 v[2:3], v[2:3], v[4:5]
	v_mov_b32_e32 v4, v2
	v_mov_b32_e32 v5, v3
	s_nop 1
	v_permlane16_swap_b32_e32 v4, v2
	v_permlane16_swap_b32_e32 v5, v3
	s_waitcnt lgkmcnt(0)
	v_pk_add_f32 v[2:3], v[2:3], v[4:5]
	v_mov_b32_e32 v4, v2
	v_mov_b32_e32 v5, v3
	s_nop 1
	v_permlane32_swap_b32_e32 v4, v2
	v_permlane32_swap_b32_e32 v5, v3
	s_and_saveexec_b64 s[36:37], s[40:41]
	s_cbranch_execz .LBB0_887
	s_waitcnt lgkmcnt(0)
	v_pk_add_f32 v[2:3], v[2:3], v[4:5]
	v_lshlrev_b64 v[4:5], 7, v[202:203]
	v_lshl_add_u64 v[4:5], s[12:13], 0, v[4:5]
	v_lshl_add_u64 v[4:5], s[30:31], 2, v[4:5]
	global_store_dwordx2 v[4:5], v[2:3], off
	s_or_b64 exec, exec, s[36:37]
	s_andn2_b64 vcc, exec, s[20:21]
	s_cbranch_vccnz .LBB0_903
	s_branch .LBB0_888
